# all optimisations, grid-barrier invalidate kept after the release (conservative ordering)
# baseline (speedup 1.0000x reference)
.LBB0_311:
	s_waitcnt lgkmcnt(0)
	v_readlane_b32 s16, v254, 56
	v_readlane_b32 s4, v252, 14
	v_readlane_b32 s5, v252, 15
	v_mov_b32_e32 v4, 1
	v_mov_b32_e32 v6, s16
	ds_read_b32 v5, v6 offset:8
	s_nop 3
	global_atomic_add v4, v3, v4, s[4:5] sc0
	s_waitcnt vmcnt(0) lgkmcnt(0)
	v_add_u32_e32 v5, 1, v5
	v_mul_lo_u32 v1, v5, v2
	v_mul_lo_u32 v8, v5, v0
	v_add_u32_e32 v4, 1, v4
	ds_write_b32 v6, v5 offset:8
	v_readlane_b32 s4, v252, 18
	v_readlane_b32 s5, v252, 19
	v_readfirstlane_b32 s20, v1
	v_readfirstlane_b32 s21, v4
	v_readfirstlane_b32 s17, v8
	s_cmp_lg_u32 s21, s20
	s_cbranch_scc1 .Lxb0_poll
	buffer_wbl2 sc1
	s_waitcnt vmcnt(0)

.Lxb0_loop:
	global_load_dword v4, v3, s[4:5] sc1
	s_waitcnt vmcnt(0)
	v_readfirstlane_b32 s21, v4
	s_cmp_ge_u32 s21, s17
	s_cbranch_scc1 .Lxb0_done
	s_sleep 1
	s_add_i32 s16, s16, 1
	s_cmp_lt_u32 s16, 0x100000
	s_cbranch_scc1 .Lxb0_loop
.Lxb0_done:
	buffer_inv sc1
.Lxb0_noinv:
	s_waitcnt vmcnt(0) lgkmcnt(0)

.Lxb1_loop:
	global_load_dword v4, v3, s[4:5] sc1
	s_waitcnt vmcnt(0)
	v_readfirstlane_b32 s21, v4
	s_cmp_ge_u32 s21, s17
	s_cbranch_scc1 .Lxb1_done
	s_sleep 1
	s_add_i32 s16, s16, 1
	s_cmp_lt_u32 s16, 0x100000
	s_cbranch_scc1 .Lxb1_loop
.Lxb1_done:
	buffer_inv sc1
.Lxb1_noinv:
	s_waitcnt vmcnt(0) lgkmcnt(0)

.Lxb2_loop:
	global_load_dword v4, v3, s[4:5] sc1
	s_waitcnt vmcnt(0)
	v_readfirstlane_b32 s21, v4
	s_cmp_ge_u32 s21, s17
	s_cbranch_scc1 .Lxb2_done
	s_sleep 1
	s_add_i32 s16, s16, 1
	s_cmp_lt_u32 s16, 0x100000
	s_cbranch_scc1 .Lxb2_loop
.Lxb2_done:
	buffer_inv sc1
.Lxb2_noinv:
	s_waitcnt vmcnt(0) lgkmcnt(0)

.Lxb3_loop:
	global_load_dword v4, v3, s[4:5] sc1
	s_waitcnt vmcnt(0)
	v_readfirstlane_b32 s21, v4
	s_cmp_ge_u32 s21, s17
	s_cbranch_scc1 .Lxb3_done
	s_sleep 1
	s_add_i32 s16, s16, 1
	s_cmp_lt_u32 s16, 0x100000
	s_cbranch_scc1 .Lxb3_loop
.Lxb3_done:
	buffer_inv sc1
.Lxb3_noinv:
	s_waitcnt vmcnt(0) lgkmcnt(0)

.Lxb4_loop:
	global_load_dword v4, v3, s[4:5] sc1
	s_waitcnt vmcnt(0)
	v_readfirstlane_b32 s21, v4
	s_cmp_ge_u32 s21, s17
	s_cbranch_scc1 .Lxb4_done
	s_sleep 1
	s_add_i32 s16, s16, 1
	s_cmp_lt_u32 s16, 0x100000
	s_cbranch_scc1 .Lxb4_loop
.Lxb4_done:
	buffer_inv sc1
.Lxb4_noinv:
	s_waitcnt vmcnt(0) lgkmcnt(0)

.Lxb5_loop:
	global_load_dword v4, v3, s[4:5] sc1
	s_waitcnt vmcnt(0)
	v_readfirstlane_b32 s21, v4
	s_cmp_ge_u32 s21, s17
	s_cbranch_scc1 .Lxb5_done
	s_sleep 1
	s_add_i32 s16, s16, 1
	s_cmp_lt_u32 s16, 0x100000
	s_cbranch_scc1 .Lxb5_loop
.Lxb5_done:
	buffer_inv sc1
.Lxb5_noinv:
	s_waitcnt vmcnt(0) lgkmcnt(0)

.Lxb6_loop:
	global_load_dword v4, v3, s[4:5] sc1
	s_waitcnt vmcnt(0)
	v_readfirstlane_b32 s21, v4
	s_cmp_ge_u32 s21, s17
	s_cbranch_scc1 .Lxb6_done
	s_sleep 1
	s_add_i32 s16, s16, 1
	s_cmp_lt_u32 s16, 0x100000
	s_cbranch_scc1 .Lxb6_loop
.Lxb6_done:
	buffer_inv sc1
.Lxb6_noinv:
	s_waitcnt vmcnt(0) lgkmcnt(0)

.Lxb7_loop:
	global_load_dword v4, v3, s[4:5] sc1
	s_waitcnt vmcnt(0)
	v_readfirstlane_b32 s21, v4
	s_cmp_ge_u32 s21, s17
	s_cbranch_scc1 .Lxb7_done
	s_sleep 1
	s_add_i32 s16, s16, 1
	s_cmp_lt_u32 s16, 0x100000
	s_cbranch_scc1 .Lxb7_loop
.Lxb7_done:
	buffer_inv sc1
.Lxb7_noinv:
	s_waitcnt vmcnt(0) lgkmcnt(0)

.Lxb8_loop:
	global_load_dword v4, v3, s[4:5] sc1
	s_waitcnt vmcnt(0)
	v_readfirstlane_b32 s21, v4
	s_cmp_ge_u32 s21, s17
	s_cbranch_scc1 .Lxb8_done
	s_sleep 1
	s_add_i32 s16, s16, 1
	s_cmp_lt_u32 s16, 0x100000
	s_cbranch_scc1 .Lxb8_loop
.Lxb8_done:
	buffer_inv sc1
.Lxb8_noinv:
	s_waitcnt vmcnt(0) lgkmcnt(0)
	s_mov_b64 s[4:5], 0
	s_getpc_b64 s[98:99]
